# input projection: waves 4-7 take the column quarter wc^1 (virtual wave id), so each SIMD hosts one rotary-embedding wave and one plain wave in Q/K tiles
# speedup vs baseline: 1.0325x; 1.0015x over previous
.LBB0_156:
	v_mov_b32_e32 v8, v214
	v_bfe_u32 v1, v8, 8, 1
	v_lshlrev_b32_e32 v1, 6, v1
	v_xor_b32_e32 v8, v8, v1
	s_cmpk_lt_i32 s2, 0x780
	s_cselect_b64 s[0:1], -1, 0
	s_cmpk_gt_i32 s2, 0x77f
	v_readfirstlane_b32 s4, v8
	s_cbranch_scc1 .LBB0_158
	s_ashr_i32 s3, s2, 31
	s_lshr_b32 s3, s3, 29
	s_add_i32 s3, s2, s3
	s_ashr_i32 s5, s3, 3
	s_and_b32 s3, s3, -8
	s_sub_i32 s3, s2, s3
	s_cmp_lt_i32 s3, 0
	s_movk_i32 s6, 0xf1
	s_cselect_b32 s6, s6, 0xf0
	s_mul_i32 s3, s3, s6
	s_add_i32 s3, s3, s5
	s_mul_hi_i32 s5, s3, 0x66666667
	s_lshr_b32 s6, s5, 31
	s_ashr_i32 s5, s5, 5
	s_add_i32 s5, s5, s6
	s_lshl_b32 s6, s5, 3
	s_mulk_i32 s5, 0x50
	s_sub_i32 s3, s3, s5
	s_bfe_i32 s5, s3, 0x80000
	s_bfe_u32 s5, s5, 0x3000c
	s_add_i32 s5, s3, s5
	s_bfe_i32 s7, s5, 0x80000
	s_and_b32 s5, s5, 0xf8
	s_sub_i32 s3, s3, s5
	s_sext_i32_i16 s7, s7
	s_sext_i32_i8 s3, s3
	s_add_i32 s81, s6, s3
	s_ashr_i32 s10, s7, 3

.LBB0_170:
	v_readfirstlane_b32 s8, v214
	v_and_b32_e32 v152, 15, v214
	v_bfe_u32 v153, v214, 4, 2
	s_lshr_b32 s8, s8, 6
	s_lshr_b32 s9, s8, 2
	s_xor_b32 s8, s8, s9
	s_and_b32 s8, s8, 3
	s_lshl_b32 s9, s9, 6
	s_lshl_b32 s11, s81, 8
	s_add_i32 s9, s9, s11
	v_add_u32_e32 v154, s9, v152
	s_cmp_lg_u32 s10, 0
	s_cbranch_scc1 .Lp1_qkv
	s_add_u32 s20, s86, 0x8000000
	s_addc_u32 s21, s87, 0
	s_lshl_b32 s9, s8, 6
	v_lshlrev_b32_e32 v155, 9, v154
	v_lshl_add_u32 v155, v153, 4, v155
	v_add_u32_e32 v155, s9, v155
	v_mov_b32_e32 v158, v155
	v_pk_mul_f32 v[124:125], v[124:125], v[248:249] op_sel_hi:[1,0]
	v_pk_mul_f32 v[126:127], v[126:127], v[248:249] op_sel_hi:[1,0]
	v_pk_mul_f32 v[120:121], v[120:121], v[248:249] op_sel_hi:[1,0]
	v_pk_mul_f32 v[122:123], v[122:123], v[248:249] op_sel_hi:[1,0]
	v_pk_mul_f32 v[116:117], v[116:117], v[248:249] op_sel_hi:[1,0]
	v_pk_mul_f32 v[118:119], v[118:119], v[248:249] op_sel_hi:[1,0]
	v_pk_mul_f32 v[112:113], v[112:113], v[248:249] op_sel_hi:[1,0]
	v_pk_mul_f32 v[114:115], v[114:115], v[248:249] op_sel_hi:[1,0]
	v_cvt_pk_bf16_f32 v124, v124, v125
	v_cvt_pk_bf16_f32 v125, v126, v127
	v_cvt_pk_bf16_f32 v126, v120, v121
	v_cvt_pk_bf16_f32 v127, v122, v123
	global_store_dwordx4 v158, v[124:127], s[20:21]
	v_cvt_pk_bf16_f32 v116, v116, v117
	v_cvt_pk_bf16_f32 v117, v118, v119
	v_cvt_pk_bf16_f32 v118, v112, v113
	v_cvt_pk_bf16_f32 v119, v114, v115
	global_store_dwordx4 v158, v[116:119], s[20:21] offset:256
	s_nop 1
	v_add_u32_e32 v158, 0x2000, v155
	v_pk_mul_f32 v[108:109], v[108:109], v[248:249] op_sel:[0,1] op_sel_hi:[1,1]
	v_pk_mul_f32 v[110:111], v[110:111], v[248:249] op_sel:[0,1] op_sel_hi:[1,1]
	v_pk_mul_f32 v[104:105], v[104:105], v[248:249] op_sel:[0,1] op_sel_hi:[1,1]
	v_pk_mul_f32 v[106:107], v[106:107], v[248:249] op_sel:[0,1] op_sel_hi:[1,1]
	v_pk_mul_f32 v[100:101], v[100:101], v[248:249] op_sel:[0,1] op_sel_hi:[1,1]
	v_pk_mul_f32 v[102:103], v[102:103], v[248:249] op_sel:[0,1] op_sel_hi:[1,1]
	v_pk_mul_f32 v[96:97], v[96:97], v[248:249] op_sel:[0,1] op_sel_hi:[1,1]
	v_pk_mul_f32 v[98:99], v[98:99], v[248:249] op_sel:[0,1] op_sel_hi:[1,1]
	v_cvt_pk_bf16_f32 v108, v108, v109
	v_cvt_pk_bf16_f32 v109, v110, v111
	v_cvt_pk_bf16_f32 v110, v104, v105
	v_cvt_pk_bf16_f32 v111, v106, v107
	global_store_dwordx4 v158, v[108:111], s[20:21]
	v_cvt_pk_bf16_f32 v100, v100, v101
	v_cvt_pk_bf16_f32 v101, v102, v103
	v_cvt_pk_bf16_f32 v102, v96, v97
	v_cvt_pk_bf16_f32 v103, v98, v99
	global_store_dwordx4 v158, v[100:103], s[20:21] offset:256
	s_nop 1
	v_add_u32_e32 v158, 0x4000, v155
	v_pk_mul_f32 v[92:93], v[92:93], v[250:251] op_sel_hi:[1,0]
	v_pk_mul_f32 v[94:95], v[94:95], v[250:251] op_sel_hi:[1,0]
	v_pk_mul_f32 v[88:89], v[88:89], v[250:251] op_sel_hi:[1,0]
	v_pk_mul_f32 v[90:91], v[90:91], v[250:251] op_sel_hi:[1,0]
	v_pk_mul_f32 v[80:81], v[80:81], v[250:251] op_sel_hi:[1,0]
	v_pk_mul_f32 v[82:83], v[82:83], v[250:251] op_sel_hi:[1,0]
	v_pk_mul_f32 v[72:73], v[72:73], v[250:251] op_sel_hi:[1,0]
	v_pk_mul_f32 v[74:75], v[74:75], v[250:251] op_sel_hi:[1,0]
	v_cvt_pk_bf16_f32 v92, v92, v93
	v_cvt_pk_bf16_f32 v93, v94, v95
	v_cvt_pk_bf16_f32 v94, v88, v89
	v_cvt_pk_bf16_f32 v95, v90, v91
	global_store_dwordx4 v158, v[92:95], s[20:21]
	v_cvt_pk_bf16_f32 v80, v80, v81
	v_cvt_pk_bf16_f32 v81, v82, v83
	v_cvt_pk_bf16_f32 v82, v72, v73
	v_cvt_pk_bf16_f32 v83, v74, v75
	global_store_dwordx4 v158, v[80:83], s[20:21] offset:256
	s_nop 1
	v_add_u32_e32 v158, 0x6000, v155
	v_pk_mul_f32 v[84:85], v[84:85], v[250:251] op_sel:[0,1] op_sel_hi:[1,1]
	v_pk_mul_f32 v[86:87], v[86:87], v[250:251] op_sel:[0,1] op_sel_hi:[1,1]
	v_pk_mul_f32 v[76:77], v[76:77], v[250:251] op_sel:[0,1] op_sel_hi:[1,1]
	v_pk_mul_f32 v[78:79], v[78:79], v[250:251] op_sel:[0,1] op_sel_hi:[1,1]
	v_pk_mul_f32 v[68:69], v[68:69], v[250:251] op_sel:[0,1] op_sel_hi:[1,1]
	v_pk_mul_f32 v[70:71], v[70:71], v[250:251] op_sel:[0,1] op_sel_hi:[1,1]
	v_pk_mul_f32 v[64:65], v[64:65], v[250:251] op_sel:[0,1] op_sel_hi:[1,1]
	v_pk_mul_f32 v[66:67], v[66:67], v[250:251] op_sel:[0,1] op_sel_hi:[1,1]
	v_cvt_pk_bf16_f32 v84, v84, v85
	v_cvt_pk_bf16_f32 v85, v86, v87
	v_cvt_pk_bf16_f32 v86, v76, v77
	v_cvt_pk_bf16_f32 v87, v78, v79
	global_store_dwordx4 v158, v[84:87], s[20:21]
	v_cvt_pk_bf16_f32 v68, v68, v69
	v_cvt_pk_bf16_f32 v69, v70, v71
	v_cvt_pk_bf16_f32 v70, v64, v65
	v_cvt_pk_bf16_f32 v71, v66, v67
	global_store_dwordx4 v158, v[68:71], s[20:21] offset:256
	s_nop 1
	v_add_u32_e32 v158, 0x10000, v155
	v_pk_mul_f32 v[60:61], v[60:61], v[252:253] op_sel_hi:[1,0]
	v_pk_mul_f32 v[62:63], v[62:63], v[252:253] op_sel_hi:[1,0]
	v_pk_mul_f32 v[56:57], v[56:57], v[252:253] op_sel_hi:[1,0]
	v_pk_mul_f32 v[58:59], v[58:59], v[252:253] op_sel_hi:[1,0]
	v_pk_mul_f32 v[52:53], v[52:53], v[252:253] op_sel_hi:[1,0]
	v_pk_mul_f32 v[54:55], v[54:55], v[252:253] op_sel_hi:[1,0]
	v_pk_mul_f32 v[48:49], v[48:49], v[252:253] op_sel_hi:[1,0]
	v_pk_mul_f32 v[50:51], v[50:51], v[252:253] op_sel_hi:[1,0]
	v_cvt_pk_bf16_f32 v60, v60, v61
	v_cvt_pk_bf16_f32 v61, v62, v63
	v_cvt_pk_bf16_f32 v62, v56, v57
	v_cvt_pk_bf16_f32 v63, v58, v59
	global_store_dwordx4 v158, v[60:63], s[20:21]
	v_cvt_pk_bf16_f32 v52, v52, v53
	v_cvt_pk_bf16_f32 v53, v54, v55
	v_cvt_pk_bf16_f32 v54, v48, v49
	v_cvt_pk_bf16_f32 v55, v50, v51
	global_store_dwordx4 v158, v[52:55], s[20:21] offset:256
	s_nop 1
	v_add_u32_e32 v158, 0x12000, v155
	v_pk_mul_f32 v[44:45], v[44:45], v[252:253] op_sel:[0,1] op_sel_hi:[1,1]
	v_pk_mul_f32 v[46:47], v[46:47], v[252:253] op_sel:[0,1] op_sel_hi:[1,1]
	v_pk_mul_f32 v[40:41], v[40:41], v[252:253] op_sel:[0,1] op_sel_hi:[1,1]
	v_pk_mul_f32 v[42:43], v[42:43], v[252:253] op_sel:[0,1] op_sel_hi:[1,1]
	v_pk_mul_f32 v[36:37], v[36:37], v[252:253] op_sel:[0,1] op_sel_hi:[1,1]
	v_pk_mul_f32 v[38:39], v[38:39], v[252:253] op_sel:[0,1] op_sel_hi:[1,1]
	v_pk_mul_f32 v[32:33], v[32:33], v[252:253] op_sel:[0,1] op_sel_hi:[1,1]
	v_pk_mul_f32 v[34:35], v[34:35], v[252:253] op_sel:[0,1] op_sel_hi:[1,1]
	v_cvt_pk_bf16_f32 v44, v44, v45
	v_cvt_pk_bf16_f32 v45, v46, v47
	v_cvt_pk_bf16_f32 v46, v40, v41
	v_cvt_pk_bf16_f32 v47, v42, v43
	global_store_dwordx4 v158, v[44:47], s[20:21]
	v_cvt_pk_bf16_f32 v36, v36, v37
	v_cvt_pk_bf16_f32 v37, v38, v39
	v_cvt_pk_bf16_f32 v38, v32, v33
	v_cvt_pk_bf16_f32 v39, v34, v35
	global_store_dwordx4 v158, v[36:39], s[20:21] offset:256
	s_nop 1
	v_add_u32_e32 v158, 0x14000, v155
	v_pk_mul_f32 v[28:29], v[28:29], v[254:255] op_sel_hi:[1,0]
	v_pk_mul_f32 v[30:31], v[30:31], v[254:255] op_sel_hi:[1,0]
	v_pk_mul_f32 v[24:25], v[24:25], v[254:255] op_sel_hi:[1,0]
	v_pk_mul_f32 v[26:27], v[26:27], v[254:255] op_sel_hi:[1,0]
	v_pk_mul_f32 v[20:21], v[20:21], v[254:255] op_sel_hi:[1,0]
	v_pk_mul_f32 v[22:23], v[22:23], v[254:255] op_sel_hi:[1,0]
	v_pk_mul_f32 v[16:17], v[16:17], v[254:255] op_sel_hi:[1,0]
	v_pk_mul_f32 v[18:19], v[18:19], v[254:255] op_sel_hi:[1,0]
	v_cvt_pk_bf16_f32 v28, v28, v29
	v_cvt_pk_bf16_f32 v29, v30, v31
	v_cvt_pk_bf16_f32 v30, v24, v25
	v_cvt_pk_bf16_f32 v31, v26, v27
	global_store_dwordx4 v158, v[28:31], s[20:21]
	v_cvt_pk_bf16_f32 v20, v20, v21
	v_cvt_pk_bf16_f32 v21, v22, v23
	v_cvt_pk_bf16_f32 v22, v16, v17
	v_cvt_pk_bf16_f32 v23, v18, v19
	global_store_dwordx4 v158, v[20:23], s[20:21] offset:256
	s_nop 1
	v_add_u32_e32 v158, 0x16000, v155
	v_pk_mul_f32 v[12:13], v[12:13], v[254:255] op_sel:[0,1] op_sel_hi:[1,1]
	v_pk_mul_f32 v[14:15], v[14:15], v[254:255] op_sel:[0,1] op_sel_hi:[1,1]
	v_pk_mul_f32 v[8:9], v[8:9], v[254:255] op_sel:[0,1] op_sel_hi:[1,1]
	v_pk_mul_f32 v[10:11], v[10:11], v[254:255] op_sel:[0,1] op_sel_hi:[1,1]
	v_pk_mul_f32 v[4:5], v[4:5], v[254:255] op_sel:[0,1] op_sel_hi:[1,1]
	v_pk_mul_f32 v[6:7], v[6:7], v[254:255] op_sel:[0,1] op_sel_hi:[1,1]
	v_pk_mul_f32 v[0:1], v[0:1], v[254:255] op_sel:[0,1] op_sel_hi:[1,1]
	v_pk_mul_f32 v[2:3], v[2:3], v[254:255] op_sel:[0,1] op_sel_hi:[1,1]
	v_cvt_pk_bf16_f32 v12, v12, v13
	v_cvt_pk_bf16_f32 v13, v14, v15
	v_cvt_pk_bf16_f32 v14, v8, v9
	v_cvt_pk_bf16_f32 v15, v10, v11
	global_store_dwordx4 v158, v[12:15], s[20:21]
	v_cvt_pk_bf16_f32 v4, v4, v5
	v_cvt_pk_bf16_f32 v5, v6, v7
	v_cvt_pk_bf16_f32 v6, v0, v1
	v_cvt_pk_bf16_f32 v7, v2, v3
	global_store_dwordx4 v158, v[4:7], s[20:21] offset:256
	s_branch .Lp1_done
